# static s_setprio 1 for waves 0-3 during the attention phase (reset at phase end)
# speedup vs baseline: 1.0050x; 1.0010x over previous
; __device__ __forceinline__ KP kp_fresh(KP k) { asm volatile("" : "+s"(k)); return k; }
; __device__ __forceinline__ int tid_fresh(int wid) { return wid * 64 + lane_id(); }
; __device__ __forceinline__ void attn_phase(LAS unsigned char* lds, KP kp, int wid0) {
;     kp = kp_fresh(kp); unsigned char* ws = kp->ws;
;     const bf16* Q = (const bf16*)(ws + WS_Q); const bf16* KV = (const bf16*)(ws + WS_KV); const bf16* KR = (const bf16*)(ws + WS_KR); bf16* O = (bf16*)(ws + WS_O);
;     const int tid = tid_fresh(wid0), lane = tid & 63, wid = tid >> 6, r32 = lane & 31, hi = lane >> 5;
;     const int key_l = tid >> 3, c8 = tid & 7;
;     const int kp2 = tid >> 4, g4 = tid & 15;
;     (void)lane;
;     for (int bh = blockIdx.x; bh < NB * NHD; bh += gridDim.x) {
;         const int b = bh >> 4, h = bh & 15, rowb = b * LL;
.LBB0_408:
	s_or_b64 exec, exec, s[2:3]
	v_readlane_b32 s0, v255, 3
	v_readlane_b32 s1, v255, 4
	s_mov_b64 s[2:3], s[88:89]
	s_andn2_b64 vcc, exec, s[0:1]
	s_waitcnt lgkmcnt(0)
	s_barrier
	v_mbcnt_lo_u32_b32 v1, -1, 0
	v_mbcnt_hi_u32_b32 v1, -1, v1
	s_cbranch_vccnz .LBB0_477
	s_load_dwordx2 s[0:1], s[2:3], 0x98
	s_cmpk_ge_u32 s61, 0x100
	s_cbranch_scc1 .Latt_prio_done
	s_setprio 1
